# v081 + residual epilogues (P3, P6', P8 final): batch-2 residual loads for row groups 4-6 issued together with batch 1 into free VGPRs, waits recounted
# speedup vs baseline: 1.0042x; 1.0025x over previous
.LBB0_505:
	v_lshl_or_b32 v168, s26, 8, v178
	s_lshl_b32 s43, s50, 8
	v_ashrrev_i32_e32 v169, 31, v168
	v_add_u32_e32 v170, s43, v176
	v_lshlrev_b64 v[206:207], 1, v[168:169]
	v_ashrrev_i32_e32 v171, 31, v170
	v_lshl_add_u64 v[172:173], s[28:29], 0, v[206:207]
	v_lshlrev_b64 v[208:209], 12, v[170:171]
	v_lshl_add_u64 v[128:129], v[172:173], 0, v[208:209]
	global_load_dwordx4 v[198:201], v[128:129], off
	global_load_dwordx4 v[202:205], v[128:129], off offset:256
	v_or_b32_e32 v128, 16, v170
	v_or_b32_e32 v130, 32, v170
	v_or_b32_e32 v132, 48, v170
	v_ashrrev_i32_e32 v129, 31, v128
	v_ashrrev_i32_e32 v131, 31, v130
	v_ashrrev_i32_e32 v133, 31, v132
	v_lshlrev_b64 v[128:129], 12, v[128:129]
	v_lshlrev_b64 v[130:131], 12, v[130:131]
	v_lshlrev_b64 v[132:133], 12, v[132:133]
	v_lshl_add_u64 v[128:129], v[172:173], 0, v[128:129]
	v_lshl_add_u64 v[130:131], v[172:173], 0, v[130:131]
	v_lshl_add_u64 v[196:197], v[172:173], 0, v[132:133]
	global_load_dwordx4 v[148:151], v[128:129], off
	global_load_dwordx4 v[144:147], v[128:129], off offset:256
	global_load_dwordx4 v[140:143], v[130:131], off
	global_load_dwordx4 v[136:139], v[130:131], off offset:256
	global_load_dwordx4 v[132:135], v[196:197], off
	s_nop 0
	global_load_dwordx4 v[128:131], v[196:197], off offset:256
	v_add_u32_e32 v238, s43, v182
	v_ashrrev_i32_e32 v239, 31, v238
	v_lshlrev_b64 v[246:247], 12, v[238:239]
	v_lshl_add_u64 v[246:247], v[172:173], 0, v[246:247]
	global_load_dwordx4 v[218:221], v[246:247], off
	global_load_dwordx4 v[222:225], v[246:247], off offset:256
	v_or_b32_e32 v246, 16, v238
	v_ashrrev_i32_e32 v247, 31, v246
	v_lshlrev_b64 v[246:247], 12, v[246:247]
	v_lshl_add_u64 v[246:247], v[172:173], 0, v[246:247]
	global_load_dwordx4 v[226:229], v[246:247], off
	global_load_dwordx4 v[230:233], v[246:247], off offset:256
	v_or_b32_e32 v246, 32, v238
	v_ashrrev_i32_e32 v247, 31, v246
	v_lshlrev_b64 v[246:247], 12, v[246:247]
	v_lshl_add_u64 v[246:247], v[172:173], 0, v[246:247]
	global_load_dwordx4 v[234:237], v[246:247], off
	global_load_dwordx4 v[242:245], v[246:247], off offset:256
	v_and_b32_e32 v196, 64, v195
	v_xor_b32_e32 v171, 16, v195
	v_add_u32_e32 v196, 64, v196
	v_xor_b32_e32 v197, 32, v195
	v_cmp_lt_i32_e32 vcc, v171, v196
	s_waitcnt vmcnt(6)
	v_lshlrev_b32_e32 v210, 16, v198
	v_cndmask_b32_e32 v171, v195, v171, vcc
	v_cmp_lt_i32_e32 vcc, v197, v196
	v_and_b32_e32 v211, 0xffff0000, v198
	v_lshlrev_b32_e32 v198, 16, v199
	v_and_b32_e32 v199, 0xffff0000, v199
	v_lshlrev_b32_e32 v212, 16, v200
	v_and_b32_e32 v213, 0xffff0000, v200
	v_lshlrev_b32_e32 v200, 16, v201
	v_and_b32_e32 v201, 0xffff0000, v201
	v_lshlrev_b32_e32 v214, 16, v202
	v_and_b32_e32 v215, 0xffff0000, v202
	v_lshlrev_b32_e32 v202, 16, v203
	v_and_b32_e32 v203, 0xffff0000, v203
	v_lshlrev_b32_e32 v216, 16, v204
	v_and_b32_e32 v217, 0xffff0000, v204
	v_lshlrev_b32_e32 v204, 16, v205
	v_and_b32_e32 v205, 0xffff0000, v205
	v_cndmask_b32_e32 v197, v195, v197, vcc
	v_pk_add_f32 v[126:127], v[126:127], v[198:199]
	v_pk_add_f32 v[124:125], v[124:125], v[210:211]
	v_pk_add_f32 v[122:123], v[122:123], v[200:201]
	v_pk_add_f32 v[120:121], v[120:121], v[212:213]
	v_pk_add_f32 v[118:119], v[118:119], v[202:203]
	v_pk_add_f32 v[116:117], v[116:117], v[214:215]
	v_pk_add_f32 v[198:199], v[114:115], v[204:205]
	v_pk_add_f32 v[200:201], v[112:113], v[216:217]
	v_lshlrev_b32_e32 v196, 2, v171
	v_lshlrev_b32_e32 v171, 2, v197
	v_cvt_pk_bf16_f32 v112, v124, v125
	v_cvt_pk_bf16_f32 v113, v126, v127
	v_cvt_pk_bf16_f32 v114, v120, v121
	v_cvt_pk_bf16_f32 v115, v122, v123
	v_mul_f32_e32 v125, v125, v125
	v_mul_f32_e32 v127, v127, v127
	v_mul_f32_e32 v121, v121, v121
	v_mul_f32_e32 v123, v123, v123
	v_mul_f32_e32 v197, v117, v117
	v_mul_f32_e32 v202, v119, v119
	v_mul_f32_e32 v203, v201, v201
	v_mul_f32_e32 v204, v199, v199
	v_fmac_f32_e32 v125, v124, v124
	v_fmac_f32_e32 v127, v126, v126
	v_fmac_f32_e32 v121, v120, v120
	v_fmac_f32_e32 v123, v122, v122
	v_fmac_f32_e32 v197, v116, v116
	v_fmac_f32_e32 v202, v118, v118
	v_fmac_f32_e32 v203, v200, v200
	v_fmac_f32_e32 v204, v198, v198
	v_add_f32_e32 v120, v125, v127
	v_add_f32_e32 v121, v121, v123
	v_add_f32_e32 v122, v197, v202
	v_add_f32_e32 v123, v203, v204
	v_add_f32_e32 v120, v120, v121
	v_add_f32_e32 v121, v122, v123
	v_add_f32_e32 v122, v120, v121
	v_mov_b32_e32 v123, v122
	s_nop 1
	v_permlane16_swap_b32_e32 v122, v123
	v_lshl_add_u64 v[120:121], s[28:29], 0, v[208:209]
	v_lshl_add_u64 v[120:121], v[120:121], 0, v[206:207]
	global_store_dwordx4 v[120:121], v[112:115], off
	s_waitcnt lgkmcnt(0)
	s_nop 0
	v_add_f32_e32 v112, v122, v123
	v_mov_b32_e32 v113, v112
	s_nop 1
	v_permlane32_swap_b32_e32 v112, v113
	v_cvt_pk_bf16_f32 v114, v116, v117
	v_cvt_pk_bf16_f32 v115, v118, v119
	v_cvt_pk_bf16_f32 v116, v200, v201
	v_cvt_pk_bf16_f32 v117, v198, v199
	global_store_dwordx4 v[120:121], v[114:117], off offset:256
	s_and_saveexec_b64 s[50:51], s[6:7]
	s_cbranch_execz .LBB0_507
	s_waitcnt lgkmcnt(0)
	v_add_f32_e32 v112, v112, v113
	ds_write_b32 v187, v112

.LBB0_513:
	s_or_b64 exec, exec, s[50:51]
	v_add_u32_e32 v64, s43, v182
	s_waitcnt lgkmcnt(0)
	v_ashrrev_i32_e32 v65, 31, v64
	v_lshlrev_b64 v[96:97], 12, v[64:65]
	v_lshl_add_u64 v[66:67], v[172:173], 0, v[96:97]
	v_or_b32_e32 v66, 16, v64
	v_or_b32_e32 v68, 32, v64
	v_or_b32_e32 v64, 48, v64
	v_ashrrev_i32_e32 v67, 31, v66
	v_ashrrev_i32_e32 v69, 31, v68
	v_ashrrev_i32_e32 v65, 31, v64
	v_lshlrev_b64 v[66:67], 12, v[66:67]
	v_lshlrev_b64 v[68:69], 12, v[68:69]
	v_lshlrev_b64 v[64:65], 12, v[64:65]
	v_lshl_add_u64 v[66:67], v[172:173], 0, v[66:67]
	v_lshl_add_u64 v[68:69], v[172:173], 0, v[68:69]
	v_lshl_add_u64 v[64:65], v[172:173], 0, v[64:65]
	s_nop 0
	global_load_dwordx4 v[68:71], v[64:65], off
	s_nop 0
	global_load_dwordx4 v[64:67], v[64:65], off offset:256
	s_waitcnt vmcnt(14)
	v_lshlrev_b32_e32 v98, 16, v218
	v_and_b32_e32 v99, 0xffff0000, v218
	v_lshlrev_b32_e32 v88, 16, v219
	v_and_b32_e32 v89, 0xffff0000, v219
	v_lshlrev_b32_e32 v100, 16, v220
	v_and_b32_e32 v101, 0xffff0000, v220
	v_lshlrev_b32_e32 v90, 16, v221
	v_and_b32_e32 v91, 0xffff0000, v221
	s_waitcnt vmcnt(14)
	v_lshlrev_b32_e32 v102, 16, v222
	v_and_b32_e32 v103, 0xffff0000, v222
	v_lshlrev_b32_e32 v92, 16, v223
	v_and_b32_e32 v93, 0xffff0000, v223
	v_lshlrev_b32_e32 v104, 16, v224
	v_and_b32_e32 v105, 0xffff0000, v224
	v_lshlrev_b32_e32 v94, 16, v225
	v_and_b32_e32 v95, 0xffff0000, v225
	v_pk_add_f32 v[62:63], v[62:63], v[88:89]
	v_pk_add_f32 v[60:61], v[60:61], v[98:99]
	v_pk_add_f32 v[58:59], v[58:59], v[90:91]
	v_pk_add_f32 v[56:57], v[56:57], v[100:101]
	v_pk_add_f32 v[54:55], v[54:55], v[92:93]
	v_pk_add_f32 v[52:53], v[52:53], v[102:103]
	v_pk_add_f32 v[88:89], v[50:51], v[94:95]
	v_pk_add_f32 v[90:91], v[48:49], v[104:105]
	v_cvt_pk_bf16_f32 v48, v60, v61
	v_cvt_pk_bf16_f32 v49, v62, v63
	v_cvt_pk_bf16_f32 v50, v56, v57
	v_cvt_pk_bf16_f32 v51, v58, v59
	v_mul_f32_e32 v61, v61, v61
	v_mul_f32_e32 v63, v63, v63
	v_mul_f32_e32 v57, v57, v57
	v_mul_f32_e32 v59, v59, v59
	v_mul_f32_e32 v92, v53, v53
	v_mul_f32_e32 v93, v55, v55
	v_mul_f32_e32 v94, v91, v91
	v_mul_f32_e32 v95, v89, v89
	v_fmac_f32_e32 v61, v60, v60
	v_fmac_f32_e32 v63, v62, v62
	v_fmac_f32_e32 v57, v56, v56
	v_fmac_f32_e32 v59, v58, v58
	v_fmac_f32_e32 v92, v52, v52
	v_fmac_f32_e32 v93, v54, v54
	v_fmac_f32_e32 v94, v90, v90
	v_fmac_f32_e32 v95, v88, v88
	v_add_f32_e32 v56, v61, v63
	v_add_f32_e32 v57, v57, v59
	v_add_f32_e32 v58, v92, v93
	v_add_f32_e32 v59, v94, v95
	v_add_f32_e32 v56, v56, v57
	v_add_f32_e32 v57, v58, v59
	v_add_f32_e32 v58, v56, v57
	v_mov_b32_e32 v59, v58
	s_nop 1
	v_permlane16_swap_b32_e32 v58, v59
	v_lshl_add_u64 v[56:57], s[28:29], 0, v[96:97]
	v_lshl_add_u64 v[56:57], v[168:169], 1, v[56:57]
	global_store_dwordx4 v[56:57], v[48:51], off
	s_waitcnt lgkmcnt(0)
	s_nop 0
	v_add_f32_e32 v48, v58, v59
	v_mov_b32_e32 v49, v48
	s_nop 1
	v_permlane32_swap_b32_e32 v48, v49
	v_cvt_pk_bf16_f32 v50, v52, v53
	v_cvt_pk_bf16_f32 v51, v54, v55
	v_cvt_pk_bf16_f32 v52, v90, v91
	v_cvt_pk_bf16_f32 v53, v88, v89
	global_store_dwordx4 v[56:57], v[50:53], off offset:256
	s_and_saveexec_b64 s[50:51], s[6:7]
	s_cbranch_execz .LBB0_515
	s_waitcnt lgkmcnt(0)
	v_add_f32_e32 v48, v48, v49
	ds_write_b32 v191, v48
.LBB0_515:
	s_or_b64 exec, exec, s[50:51]
	s_waitcnt vmcnt(14)
	v_lshlrev_b32_e32 v50, 16, v226
	v_and_b32_e32 v51, 0xffff0000, v226
	v_lshlrev_b32_e32 v52, 16, v227
	v_and_b32_e32 v53, 0xffff0000, v227
	v_lshlrev_b32_e32 v54, 16, v228
	v_and_b32_e32 v55, 0xffff0000, v228
	v_pk_add_f32 v[44:45], v[44:45], v[50:51]
	v_pk_add_f32 v[46:47], v[46:47], v[52:53]
	v_pk_add_f32 v[52:53], v[40:41], v[54:55]
	v_cvt_pk_bf16_f32 v40, v44, v45
	v_mul_f32_e32 v45, v45, v45
	v_lshlrev_b32_e32 v56, 16, v229
	v_and_b32_e32 v57, 0xffff0000, v229
	v_fmac_f32_e32 v45, v44, v44
	v_mul_f32_e32 v44, v47, v47
	v_pk_add_f32 v[50:51], v[42:43], v[56:57]
	v_fmac_f32_e32 v44, v46, v46
	v_cvt_pk_bf16_f32 v41, v46, v47
	v_add_f32_e32 v44, v45, v44
	v_mul_f32_e32 v45, v53, v53
	v_mul_f32_e32 v46, v51, v51
	v_fmac_f32_e32 v45, v52, v52
	v_fmac_f32_e32 v46, v50, v50
	v_add_f32_e32 v45, v45, v46
	v_add_f32_e32 v54, v44, v45
	s_waitcnt vmcnt(14)
	v_lshlrev_b32_e32 v44, 16, v230
	v_and_b32_e32 v45, 0xffff0000, v230
	v_lshlrev_b32_e32 v46, 16, v231
	v_and_b32_e32 v47, 0xffff0000, v231
	v_cvt_pk_bf16_f32 v43, v50, v51
	v_lshlrev_b32_e32 v50, 16, v232
	v_and_b32_e32 v51, 0xffff0000, v232
	v_pk_add_f32 v[38:39], v[38:39], v[46:47]
	v_pk_add_f32 v[36:37], v[36:37], v[44:45]
	v_cvt_pk_bf16_f32 v42, v52, v53
	v_lshlrev_b32_e32 v52, 16, v233
	v_and_b32_e32 v53, 0xffff0000, v233
	v_pk_add_f32 v[46:47], v[32:33], v[50:51]
	v_mul_f32_e32 v32, v37, v37
	v_mul_f32_e32 v33, v39, v39
	v_pk_add_f32 v[44:45], v[34:35], v[52:53]
	v_fmac_f32_e32 v32, v36, v36
	v_fmac_f32_e32 v33, v38, v38
	v_add_f32_e32 v32, v32, v33
	v_mul_f32_e32 v33, v47, v47
	v_mul_f32_e32 v34, v45, v45
	v_fmac_f32_e32 v33, v46, v46
	v_fmac_f32_e32 v34, v44, v44
	v_add_f32_e32 v33, v33, v34
	v_add_f32_e32 v32, v32, v33
	v_add_f32_e32 v35, v54, v32
	v_mov_b32_e32 v50, v35
	s_nop 1
	v_permlane16_swap_b32_e32 v35, v50
	v_add_u32_e32 v48, 0x90, v170
	s_waitcnt lgkmcnt(1)
	v_ashrrev_i32_e32 v49, 31, v48
	v_lshlrev_b64 v[48:49], 12, v[48:49]
	v_lshl_add_u64 v[32:33], s[28:29], 0, v[48:49]
	v_lshl_add_u64 v[48:49], v[168:169], 1, v[32:33]
	s_waitcnt lgkmcnt(0)
	v_add_f32_e32 v32, v35, v50
	v_mov_b32_e32 v33, v32
	s_nop 1
	v_permlane32_swap_b32_e32 v32, v33
	v_cvt_pk_bf16_f32 v34, v36, v37
	v_cvt_pk_bf16_f32 v35, v38, v39
	v_cvt_pk_bf16_f32 v36, v46, v47
	v_cvt_pk_bf16_f32 v37, v44, v45
	global_store_dwordx4 v[48:49], v[40:43], off
	global_store_dwordx4 v[48:49], v[34:37], off offset:256
	s_and_saveexec_b64 s[50:51], s[6:7]
	s_cbranch_execz .LBB0_517
	s_waitcnt lgkmcnt(0)
	v_add_f32_e32 v32, v32, v33
	ds_write_b32 v187, v32 offset:2304
.LBB0_517:
	s_or_b64 exec, exec, s[50:51]
	s_waitcnt vmcnt(14)
	v_lshlrev_b32_e32 v34, 16, v234
	v_and_b32_e32 v35, 0xffff0000, v234
	v_lshlrev_b32_e32 v36, 16, v235
	v_and_b32_e32 v37, 0xffff0000, v235
	v_lshlrev_b32_e32 v38, 16, v236
	v_and_b32_e32 v39, 0xffff0000, v236
	v_pk_add_f32 v[28:29], v[28:29], v[34:35]
	v_pk_add_f32 v[30:31], v[30:31], v[36:37]
	v_pk_add_f32 v[36:37], v[24:25], v[38:39]
	v_cvt_pk_bf16_f32 v24, v28, v29
	v_mul_f32_e32 v29, v29, v29
	v_lshlrev_b32_e32 v40, 16, v237
	v_and_b32_e32 v41, 0xffff0000, v237
	v_fmac_f32_e32 v29, v28, v28
	v_mul_f32_e32 v28, v31, v31
	v_pk_add_f32 v[34:35], v[26:27], v[40:41]
	v_fmac_f32_e32 v28, v30, v30
	v_cvt_pk_bf16_f32 v25, v30, v31
	v_add_f32_e32 v28, v29, v28
	v_mul_f32_e32 v29, v37, v37
	v_mul_f32_e32 v30, v35, v35
	v_fmac_f32_e32 v29, v36, v36
	v_fmac_f32_e32 v30, v34, v34
	v_add_f32_e32 v29, v29, v30
	v_add_f32_e32 v38, v28, v29
	s_waitcnt vmcnt(14)
	v_lshlrev_b32_e32 v28, 16, v242
	v_and_b32_e32 v29, 0xffff0000, v242
	v_lshlrev_b32_e32 v30, 16, v243
	v_and_b32_e32 v31, 0xffff0000, v243
	v_cvt_pk_bf16_f32 v27, v34, v35
	v_lshlrev_b32_e32 v34, 16, v244
	v_and_b32_e32 v35, 0xffff0000, v244
	v_pk_add_f32 v[22:23], v[22:23], v[30:31]
	v_pk_add_f32 v[20:21], v[20:21], v[28:29]
	v_cvt_pk_bf16_f32 v26, v36, v37
	v_lshlrev_b32_e32 v36, 16, v245
	v_and_b32_e32 v37, 0xffff0000, v245
	v_pk_add_f32 v[30:31], v[16:17], v[34:35]
	v_mul_f32_e32 v16, v21, v21
	v_mul_f32_e32 v17, v23, v23
	v_pk_add_f32 v[28:29], v[18:19], v[36:37]
	v_fmac_f32_e32 v16, v20, v20
	v_fmac_f32_e32 v17, v22, v22
	v_add_f32_e32 v16, v16, v17
	v_mul_f32_e32 v17, v31, v31
	v_mul_f32_e32 v18, v29, v29
	v_fmac_f32_e32 v17, v30, v30
	v_fmac_f32_e32 v18, v28, v28
	v_add_f32_e32 v17, v17, v18
	v_add_f32_e32 v16, v16, v17
	v_add_f32_e32 v19, v38, v16
	v_mov_b32_e32 v34, v19
	s_nop 1
	v_permlane16_swap_b32_e32 v19, v34
	v_add_u32_e32 v32, 0xa0, v170
	s_waitcnt lgkmcnt(1)
	v_ashrrev_i32_e32 v33, 31, v32
	v_lshlrev_b64 v[32:33], 12, v[32:33]
	v_lshl_add_u64 v[16:17], s[28:29], 0, v[32:33]
	v_lshl_add_u64 v[32:33], v[168:169], 1, v[16:17]
	s_waitcnt lgkmcnt(0)
	v_add_f32_e32 v16, v19, v34
	v_mov_b32_e32 v17, v16
	s_nop 1
	v_permlane32_swap_b32_e32 v16, v17
	v_cvt_pk_bf16_f32 v18, v20, v21
	v_cvt_pk_bf16_f32 v19, v22, v23
	v_cvt_pk_bf16_f32 v20, v30, v31
	v_cvt_pk_bf16_f32 v21, v28, v29
	global_store_dwordx4 v[32:33], v[24:27], off
	global_store_dwordx4 v[32:33], v[18:21], off offset:256
	s_and_saveexec_b64 s[50:51], s[6:7]
	s_cbranch_execz .LBB0_519
	s_waitcnt lgkmcnt(0)
	v_add_f32_e32 v16, v16, v17
	ds_write_b32 v187, v16 offset:2560

.LBB0_710:
	v_lshl_or_b32 v164, s26, 8, v172
	s_lshl_b32 s41, s48, 8
	v_ashrrev_i32_e32 v165, 31, v164
	v_add_u32_e32 v166, s41, v170
	v_lshlrev_b64 v[202:203], 1, v[164:165]
	v_ashrrev_i32_e32 v167, 31, v166
	v_lshl_add_u64 v[168:169], s[28:29], 0, v[202:203]
	v_lshlrev_b64 v[204:205], 12, v[166:167]
	v_lshl_add_u64 v[128:129], v[168:169], 0, v[204:205]
	global_load_dwordx4 v[194:197], v[128:129], off
	global_load_dwordx4 v[198:201], v[128:129], off offset:256
	v_or_b32_e32 v128, 16, v166
	v_or_b32_e32 v130, 32, v166
	v_or_b32_e32 v132, 48, v166
	v_ashrrev_i32_e32 v129, 31, v128
	v_ashrrev_i32_e32 v131, 31, v130
	v_ashrrev_i32_e32 v133, 31, v132
	v_lshlrev_b64 v[128:129], 12, v[128:129]
	v_lshlrev_b64 v[130:131], 12, v[130:131]
	v_lshlrev_b64 v[132:133], 12, v[132:133]
	v_lshl_add_u64 v[128:129], v[168:169], 0, v[128:129]
	v_lshl_add_u64 v[130:131], v[168:169], 0, v[130:131]
	v_lshl_add_u64 v[192:193], v[168:169], 0, v[132:133]
	global_load_dwordx4 v[148:151], v[128:129], off
	global_load_dwordx4 v[144:147], v[128:129], off offset:256
	global_load_dwordx4 v[140:143], v[130:131], off
	global_load_dwordx4 v[136:139], v[130:131], off offset:256
	global_load_dwordx4 v[132:135], v[192:193], off
	s_nop 0
	global_load_dwordx4 v[128:131], v[192:193], off offset:256
	v_add_u32_e32 v238, s41, v178
	v_ashrrev_i32_e32 v239, 31, v238
	v_lshlrev_b64 v[246:247], 12, v[238:239]
	v_lshl_add_u64 v[246:247], v[168:169], 0, v[246:247]
	global_load_dwordx4 v[218:221], v[246:247], off
	global_load_dwordx4 v[222:225], v[246:247], off offset:256
	v_or_b32_e32 v246, 16, v238
	v_ashrrev_i32_e32 v247, 31, v246
	v_lshlrev_b64 v[246:247], 12, v[246:247]
	v_lshl_add_u64 v[246:247], v[168:169], 0, v[246:247]
	global_load_dwordx4 v[226:229], v[246:247], off
	global_load_dwordx4 v[230:233], v[246:247], off offset:256
	v_or_b32_e32 v246, 32, v238
	v_ashrrev_i32_e32 v247, 31, v246
	v_lshlrev_b64 v[246:247], 12, v[246:247]
	v_lshl_add_u64 v[246:247], v[168:169], 0, v[246:247]
	global_load_dwordx4 v[234:237], v[246:247], off
	global_load_dwordx4 v[242:245], v[246:247], off offset:256
	v_and_b32_e32 v192, 64, v191
	v_xor_b32_e32 v167, 16, v191
	v_add_u32_e32 v192, 64, v192
	v_xor_b32_e32 v193, 32, v191
	v_cmp_lt_i32_e32 vcc, v167, v192
	s_waitcnt vmcnt(6)
	v_lshlrev_b32_e32 v206, 16, v194
	v_cndmask_b32_e32 v167, v191, v167, vcc
	v_cmp_lt_i32_e32 vcc, v193, v192
	v_and_b32_e32 v207, 0xffff0000, v194
	v_lshlrev_b32_e32 v194, 16, v195
	v_and_b32_e32 v195, 0xffff0000, v195
	v_lshlrev_b32_e32 v208, 16, v196
	v_and_b32_e32 v209, 0xffff0000, v196
	v_lshlrev_b32_e32 v196, 16, v197
	v_and_b32_e32 v197, 0xffff0000, v197
	v_lshlrev_b32_e32 v210, 16, v198
	v_and_b32_e32 v211, 0xffff0000, v198
	v_lshlrev_b32_e32 v198, 16, v199
	v_and_b32_e32 v199, 0xffff0000, v199
	v_lshlrev_b32_e32 v212, 16, v200
	v_and_b32_e32 v213, 0xffff0000, v200
	v_lshlrev_b32_e32 v200, 16, v201
	v_and_b32_e32 v201, 0xffff0000, v201
	v_cndmask_b32_e32 v193, v191, v193, vcc
	v_pk_add_f32 v[126:127], v[126:127], v[194:195]
	v_pk_add_f32 v[124:125], v[124:125], v[206:207]
	v_pk_add_f32 v[122:123], v[122:123], v[196:197]
	v_pk_add_f32 v[120:121], v[120:121], v[208:209]
	v_pk_add_f32 v[118:119], v[118:119], v[198:199]
	v_pk_add_f32 v[116:117], v[116:117], v[210:211]
	v_pk_add_f32 v[194:195], v[114:115], v[200:201]
	v_pk_add_f32 v[196:197], v[112:113], v[212:213]
	v_lshlrev_b32_e32 v192, 2, v167
	v_lshlrev_b32_e32 v167, 2, v193
	v_cvt_pk_bf16_f32 v112, v124, v125
	v_cvt_pk_bf16_f32 v113, v126, v127
	v_cvt_pk_bf16_f32 v114, v120, v121
	v_cvt_pk_bf16_f32 v115, v122, v123
	v_mul_f32_e32 v125, v125, v125
	v_mul_f32_e32 v127, v127, v127
	v_mul_f32_e32 v121, v121, v121
	v_mul_f32_e32 v123, v123, v123
	v_mul_f32_e32 v193, v117, v117
	v_mul_f32_e32 v198, v119, v119
	v_mul_f32_e32 v199, v197, v197
	v_mul_f32_e32 v200, v195, v195
	v_fmac_f32_e32 v125, v124, v124
	v_fmac_f32_e32 v127, v126, v126
	v_fmac_f32_e32 v121, v120, v120
	v_fmac_f32_e32 v123, v122, v122
	v_fmac_f32_e32 v193, v116, v116
	v_fmac_f32_e32 v198, v118, v118
	v_fmac_f32_e32 v199, v196, v196
	v_fmac_f32_e32 v200, v194, v194
	v_add_f32_e32 v120, v125, v127
	v_add_f32_e32 v121, v121, v123
	v_add_f32_e32 v122, v193, v198
	v_add_f32_e32 v123, v199, v200
	v_add_f32_e32 v120, v120, v121
	v_add_f32_e32 v121, v122, v123
	v_add_f32_e32 v122, v120, v121
	v_mov_b32_e32 v123, v122
	s_nop 1
	v_permlane16_swap_b32_e32 v122, v123
	v_lshl_add_u64 v[120:121], s[28:29], 0, v[204:205]
	v_lshl_add_u64 v[120:121], v[120:121], 0, v[202:203]
	global_store_dwordx4 v[120:121], v[112:115], off
	s_waitcnt lgkmcnt(0)
	s_nop 0
	v_add_f32_e32 v112, v122, v123
	v_mov_b32_e32 v113, v112
	s_nop 1
	v_permlane32_swap_b32_e32 v112, v113
	v_cvt_pk_bf16_f32 v114, v116, v117
	v_cvt_pk_bf16_f32 v115, v118, v119
	v_cvt_pk_bf16_f32 v116, v196, v197
	v_cvt_pk_bf16_f32 v117, v194, v195
	global_store_dwordx4 v[120:121], v[114:117], off offset:256
	s_and_saveexec_b64 s[48:49], s[6:7]
	s_cbranch_execz .LBB0_712
	s_waitcnt lgkmcnt(0)
	v_add_f32_e32 v112, v112, v113
	ds_write_b32 v183, v112

.LBB0_718:
	s_or_b64 exec, exec, s[48:49]
	v_add_u32_e32 v64, s41, v178
	s_waitcnt lgkmcnt(0)
	v_ashrrev_i32_e32 v65, 31, v64
	v_lshlrev_b64 v[96:97], 12, v[64:65]
	v_lshl_add_u64 v[66:67], v[168:169], 0, v[96:97]
	v_or_b32_e32 v66, 16, v64
	v_or_b32_e32 v68, 32, v64
	v_or_b32_e32 v64, 48, v64
	v_ashrrev_i32_e32 v67, 31, v66
	v_ashrrev_i32_e32 v69, 31, v68
	v_ashrrev_i32_e32 v65, 31, v64
	v_lshlrev_b64 v[66:67], 12, v[66:67]
	v_lshlrev_b64 v[68:69], 12, v[68:69]
	v_lshlrev_b64 v[64:65], 12, v[64:65]
	v_lshl_add_u64 v[66:67], v[168:169], 0, v[66:67]
	v_lshl_add_u64 v[68:69], v[168:169], 0, v[68:69]
	v_lshl_add_u64 v[64:65], v[168:169], 0, v[64:65]
	s_nop 0
	global_load_dwordx4 v[68:71], v[64:65], off
	s_nop 0
	global_load_dwordx4 v[64:67], v[64:65], off offset:256
	s_waitcnt vmcnt(14)
	v_lshlrev_b32_e32 v98, 16, v218
	v_and_b32_e32 v99, 0xffff0000, v218
	v_lshlrev_b32_e32 v88, 16, v219
	v_and_b32_e32 v89, 0xffff0000, v219
	v_lshlrev_b32_e32 v100, 16, v220
	v_and_b32_e32 v101, 0xffff0000, v220
	v_lshlrev_b32_e32 v90, 16, v221
	v_and_b32_e32 v91, 0xffff0000, v221
	s_waitcnt vmcnt(14)
	v_lshlrev_b32_e32 v102, 16, v222
	v_and_b32_e32 v103, 0xffff0000, v222
	v_lshlrev_b32_e32 v92, 16, v223
	v_and_b32_e32 v93, 0xffff0000, v223
	v_lshlrev_b32_e32 v104, 16, v224
	v_and_b32_e32 v105, 0xffff0000, v224
	v_lshlrev_b32_e32 v94, 16, v225
	v_and_b32_e32 v95, 0xffff0000, v225
	v_pk_add_f32 v[62:63], v[62:63], v[88:89]
	v_pk_add_f32 v[60:61], v[60:61], v[98:99]
	v_pk_add_f32 v[58:59], v[58:59], v[90:91]
	v_pk_add_f32 v[56:57], v[56:57], v[100:101]
	v_pk_add_f32 v[54:55], v[54:55], v[92:93]
	v_pk_add_f32 v[52:53], v[52:53], v[102:103]
	v_pk_add_f32 v[88:89], v[50:51], v[94:95]
	v_pk_add_f32 v[90:91], v[48:49], v[104:105]
	v_cvt_pk_bf16_f32 v48, v60, v61
	v_cvt_pk_bf16_f32 v49, v62, v63
	v_cvt_pk_bf16_f32 v50, v56, v57
	v_cvt_pk_bf16_f32 v51, v58, v59
	v_mul_f32_e32 v61, v61, v61
	v_mul_f32_e32 v63, v63, v63
	v_mul_f32_e32 v57, v57, v57
	v_mul_f32_e32 v59, v59, v59
	v_mul_f32_e32 v92, v53, v53
	v_mul_f32_e32 v93, v55, v55
	v_mul_f32_e32 v94, v91, v91
	v_mul_f32_e32 v95, v89, v89
	v_fmac_f32_e32 v61, v60, v60
	v_fmac_f32_e32 v63, v62, v62
	v_fmac_f32_e32 v57, v56, v56
	v_fmac_f32_e32 v59, v58, v58
	v_fmac_f32_e32 v92, v52, v52
	v_fmac_f32_e32 v93, v54, v54
	v_fmac_f32_e32 v94, v90, v90
	v_fmac_f32_e32 v95, v88, v88
	v_add_f32_e32 v56, v61, v63
	v_add_f32_e32 v57, v57, v59
	v_add_f32_e32 v58, v92, v93
	v_add_f32_e32 v59, v94, v95
	v_add_f32_e32 v56, v56, v57
	v_add_f32_e32 v57, v58, v59
	v_add_f32_e32 v58, v56, v57
	v_mov_b32_e32 v59, v58
	s_nop 1
	v_permlane16_swap_b32_e32 v58, v59
	v_lshl_add_u64 v[56:57], s[28:29], 0, v[96:97]
	v_lshl_add_u64 v[56:57], v[164:165], 1, v[56:57]
	global_store_dwordx4 v[56:57], v[48:51], off
	s_waitcnt lgkmcnt(0)
	s_nop 0
	v_add_f32_e32 v48, v58, v59
	v_mov_b32_e32 v49, v48
	s_nop 1
	v_permlane32_swap_b32_e32 v48, v49
	v_cvt_pk_bf16_f32 v50, v52, v53
	v_cvt_pk_bf16_f32 v51, v54, v55
	v_cvt_pk_bf16_f32 v52, v90, v91
	v_cvt_pk_bf16_f32 v53, v88, v89
	global_store_dwordx4 v[56:57], v[50:53], off offset:256
	s_and_saveexec_b64 s[48:49], s[6:7]
	s_cbranch_execz .LBB0_720
	s_waitcnt lgkmcnt(0)
	v_add_f32_e32 v48, v48, v49
	ds_write_b32 v187, v48
.LBB0_720:
	s_or_b64 exec, exec, s[48:49]
	s_waitcnt vmcnt(14)
	v_lshlrev_b32_e32 v50, 16, v226
	v_and_b32_e32 v51, 0xffff0000, v226
	v_lshlrev_b32_e32 v52, 16, v227
	v_and_b32_e32 v53, 0xffff0000, v227
	v_lshlrev_b32_e32 v54, 16, v228
	v_and_b32_e32 v55, 0xffff0000, v228
	v_pk_add_f32 v[44:45], v[44:45], v[50:51]
	v_pk_add_f32 v[46:47], v[46:47], v[52:53]
	v_pk_add_f32 v[52:53], v[40:41], v[54:55]
	v_cvt_pk_bf16_f32 v40, v44, v45
	v_mul_f32_e32 v45, v45, v45
	v_lshlrev_b32_e32 v56, 16, v229
	v_and_b32_e32 v57, 0xffff0000, v229
	v_fmac_f32_e32 v45, v44, v44
	v_mul_f32_e32 v44, v47, v47
	v_pk_add_f32 v[50:51], v[42:43], v[56:57]
	v_fmac_f32_e32 v44, v46, v46
	v_cvt_pk_bf16_f32 v41, v46, v47
	v_add_f32_e32 v44, v45, v44
	v_mul_f32_e32 v45, v53, v53
	v_mul_f32_e32 v46, v51, v51
	v_fmac_f32_e32 v45, v52, v52
	v_fmac_f32_e32 v46, v50, v50
	v_add_f32_e32 v45, v45, v46
	v_add_f32_e32 v54, v44, v45
	s_waitcnt vmcnt(14)
	v_lshlrev_b32_e32 v44, 16, v230
	v_and_b32_e32 v45, 0xffff0000, v230
	v_lshlrev_b32_e32 v46, 16, v231
	v_and_b32_e32 v47, 0xffff0000, v231
	v_cvt_pk_bf16_f32 v43, v50, v51
	v_lshlrev_b32_e32 v50, 16, v232
	v_and_b32_e32 v51, 0xffff0000, v232
	v_pk_add_f32 v[38:39], v[38:39], v[46:47]
	v_pk_add_f32 v[36:37], v[36:37], v[44:45]
	v_cvt_pk_bf16_f32 v42, v52, v53
	v_lshlrev_b32_e32 v52, 16, v233
	v_and_b32_e32 v53, 0xffff0000, v233
	v_pk_add_f32 v[46:47], v[32:33], v[50:51]
	v_mul_f32_e32 v32, v37, v37
	v_mul_f32_e32 v33, v39, v39
	v_pk_add_f32 v[44:45], v[34:35], v[52:53]
	v_fmac_f32_e32 v32, v36, v36
	v_fmac_f32_e32 v33, v38, v38
	v_add_f32_e32 v32, v32, v33
	v_mul_f32_e32 v33, v47, v47
	v_mul_f32_e32 v34, v45, v45
	v_fmac_f32_e32 v33, v46, v46
	v_fmac_f32_e32 v34, v44, v44
	v_add_f32_e32 v33, v33, v34
	v_add_f32_e32 v32, v32, v33
	v_add_f32_e32 v35, v54, v32
	v_mov_b32_e32 v50, v35
	s_nop 1
	v_permlane16_swap_b32_e32 v35, v50
	v_add_u32_e32 v48, 0x90, v166
	s_waitcnt lgkmcnt(1)
	v_ashrrev_i32_e32 v49, 31, v48
	v_lshlrev_b64 v[48:49], 12, v[48:49]
	v_lshl_add_u64 v[32:33], s[28:29], 0, v[48:49]
	v_lshl_add_u64 v[48:49], v[164:165], 1, v[32:33]
	s_waitcnt lgkmcnt(0)
	v_add_f32_e32 v32, v35, v50
	v_mov_b32_e32 v33, v32
	s_nop 1
	v_permlane32_swap_b32_e32 v32, v33
	v_cvt_pk_bf16_f32 v34, v36, v37
	v_cvt_pk_bf16_f32 v35, v38, v39
	v_cvt_pk_bf16_f32 v36, v46, v47
	v_cvt_pk_bf16_f32 v37, v44, v45
	global_store_dwordx4 v[48:49], v[40:43], off
	global_store_dwordx4 v[48:49], v[34:37], off offset:256
	s_and_saveexec_b64 s[48:49], s[6:7]
	s_cbranch_execz .LBB0_722
	s_waitcnt lgkmcnt(0)
	v_add_f32_e32 v32, v32, v33
	ds_write_b32 v183, v32 offset:2304
.LBB0_722:
	s_or_b64 exec, exec, s[48:49]
	s_waitcnt vmcnt(14)
	v_lshlrev_b32_e32 v34, 16, v234
	v_and_b32_e32 v35, 0xffff0000, v234
	v_lshlrev_b32_e32 v36, 16, v235
	v_and_b32_e32 v37, 0xffff0000, v235
	v_lshlrev_b32_e32 v38, 16, v236
	v_and_b32_e32 v39, 0xffff0000, v236
	v_pk_add_f32 v[28:29], v[28:29], v[34:35]
	v_pk_add_f32 v[30:31], v[30:31], v[36:37]
	v_pk_add_f32 v[36:37], v[24:25], v[38:39]
	v_cvt_pk_bf16_f32 v24, v28, v29
	v_mul_f32_e32 v29, v29, v29
	v_lshlrev_b32_e32 v40, 16, v237
	v_and_b32_e32 v41, 0xffff0000, v237
	v_fmac_f32_e32 v29, v28, v28
	v_mul_f32_e32 v28, v31, v31
	v_pk_add_f32 v[34:35], v[26:27], v[40:41]
	v_fmac_f32_e32 v28, v30, v30
	v_cvt_pk_bf16_f32 v25, v30, v31
	v_add_f32_e32 v28, v29, v28
	v_mul_f32_e32 v29, v37, v37
	v_mul_f32_e32 v30, v35, v35
	v_fmac_f32_e32 v29, v36, v36
	v_fmac_f32_e32 v30, v34, v34
	v_add_f32_e32 v29, v29, v30
	v_add_f32_e32 v38, v28, v29
	s_waitcnt vmcnt(14)
	v_lshlrev_b32_e32 v28, 16, v242
	v_and_b32_e32 v29, 0xffff0000, v242
	v_lshlrev_b32_e32 v30, 16, v243
	v_and_b32_e32 v31, 0xffff0000, v243
	v_cvt_pk_bf16_f32 v27, v34, v35
	v_lshlrev_b32_e32 v34, 16, v244
	v_and_b32_e32 v35, 0xffff0000, v244
	v_pk_add_f32 v[22:23], v[22:23], v[30:31]
	v_pk_add_f32 v[20:21], v[20:21], v[28:29]
	v_cvt_pk_bf16_f32 v26, v36, v37
	v_lshlrev_b32_e32 v36, 16, v245
	v_and_b32_e32 v37, 0xffff0000, v245
	v_pk_add_f32 v[30:31], v[16:17], v[34:35]
	v_mul_f32_e32 v16, v21, v21
	v_mul_f32_e32 v17, v23, v23
	v_pk_add_f32 v[28:29], v[18:19], v[36:37]
	v_fmac_f32_e32 v16, v20, v20
	v_fmac_f32_e32 v17, v22, v22
	v_add_f32_e32 v16, v16, v17
	v_mul_f32_e32 v17, v31, v31
	v_mul_f32_e32 v18, v29, v29
	v_fmac_f32_e32 v17, v30, v30
	v_fmac_f32_e32 v18, v28, v28
	v_add_f32_e32 v17, v17, v18
	v_add_f32_e32 v16, v16, v17
	v_add_f32_e32 v19, v38, v16
	v_mov_b32_e32 v34, v19
	s_nop 1
	v_permlane16_swap_b32_e32 v19, v34
	v_add_u32_e32 v32, 0xa0, v166
	s_waitcnt lgkmcnt(1)
	v_ashrrev_i32_e32 v33, 31, v32
	v_lshlrev_b64 v[32:33], 12, v[32:33]
	v_lshl_add_u64 v[16:17], s[28:29], 0, v[32:33]
	v_lshl_add_u64 v[32:33], v[164:165], 1, v[16:17]
	s_waitcnt lgkmcnt(0)
	v_add_f32_e32 v16, v19, v34
	v_mov_b32_e32 v17, v16
	s_nop 1
	v_permlane32_swap_b32_e32 v16, v17
	v_cvt_pk_bf16_f32 v18, v20, v21
	v_cvt_pk_bf16_f32 v19, v22, v23
	v_cvt_pk_bf16_f32 v20, v30, v31
	v_cvt_pk_bf16_f32 v21, v28, v29
	global_store_dwordx4 v[32:33], v[24:27], off
	global_store_dwordx4 v[32:33], v[18:21], off offset:256
	s_and_saveexec_b64 s[48:49], s[6:7]
	s_cbranch_execz .LBB0_724
	s_waitcnt lgkmcnt(0)
	v_add_f32_e32 v16, v16, v17
	ds_write_b32 v183, v16 offset:2560

.LBB0_978:
	v_lshrrev_b32_e32 v128, 1, v182
	v_and_b32_e32 v128, 56, v128
	s_lshl_b32 s24, s61, 8
	v_add_u32_e32 v185, s43, v128
	v_add_u32_e32 v172, s24, v183
	v_lshlrev_b32_e32 v160, 1, v185
	v_ashrrev_i32_e32 v173, 31, v172
	v_lshl_add_u64 v[176:177], s[28:29], 0, v[160:161]
	v_lshlrev_b64 v[128:129], 12, v[172:173]
	v_lshl_add_u64 v[128:129], v[176:177], 0, v[128:129]
	global_load_dwordx4 v[166:169], v[128:129], off
	global_load_dwordx4 v[186:189], v[128:129], off offset:256
	v_or_b32_e32 v128, 16, v172
	v_or_b32_e32 v130, 32, v172
	v_or_b32_e32 v132, 48, v172
	v_ashrrev_i32_e32 v129, 31, v128
	v_ashrrev_i32_e32 v131, 31, v130
	v_ashrrev_i32_e32 v133, 31, v132
	v_lshlrev_b64 v[128:129], 12, v[128:129]
	v_lshlrev_b64 v[130:131], 12, v[130:131]
	v_lshlrev_b64 v[132:133], 12, v[132:133]
	v_lshl_add_u64 v[128:129], v[176:177], 0, v[128:129]
	v_lshl_add_u64 v[130:131], v[176:177], 0, v[130:131]
	v_lshl_add_u64 v[170:171], v[176:177], 0, v[132:133]
	global_load_dwordx4 v[148:151], v[128:129], off
	global_load_dwordx4 v[144:147], v[128:129], off offset:256
	global_load_dwordx4 v[140:143], v[130:131], off
	global_load_dwordx4 v[136:139], v[130:131], off offset:256
	global_load_dwordx4 v[132:135], v[170:171], off
	s_nop 0
	global_load_dwordx4 v[128:131], v[170:171], off offset:256
	v_add_u32_e32 v238, 0x80, v172
	v_ashrrev_i32_e32 v239, 31, v238
	v_lshlrev_b64 v[246:247], 12, v[238:239]
	v_lshl_add_u64 v[246:247], v[176:177], 0, v[246:247]
	global_load_dwordx4 v[218:221], v[246:247], off
	global_load_dwordx4 v[222:225], v[246:247], off offset:256
	v_add_u32_e32 v238, 0x90, v172
	v_ashrrev_i32_e32 v239, 31, v238
	v_lshlrev_b64 v[246:247], 12, v[238:239]
	v_lshl_add_u64 v[246:247], v[176:177], 0, v[246:247]
	global_load_dwordx4 v[226:229], v[246:247], off
	global_load_dwordx4 v[230:233], v[246:247], off offset:256
	v_add_u32_e32 v238, 0xa0, v172
	v_ashrrev_i32_e32 v239, 31, v238
	v_lshlrev_b64 v[246:247], 12, v[238:239]
	v_lshl_add_u64 v[246:247], v[176:177], 0, v[246:247]
	global_load_dwordx4 v[234:237], v[246:247], off
	global_load_dwordx4 v[242:245], v[246:247], off offset:256
	v_and_b32_e32 v170, 64, v182
	v_add_u32_e32 v194, 64, v170
	v_xor_b32_e32 v160, 16, v182
	v_cmp_lt_i32_e32 vcc, v160, v194
	s_waitcnt vmcnt(6)
	v_lshlrev_b32_e32 v170, 16, v166
	v_and_b32_e32 v171, 0xffff0000, v166
	v_lshlrev_b32_e32 v166, 16, v167
	v_and_b32_e32 v167, 0xffff0000, v167
	v_lshlrev_b32_e32 v174, 16, v168
	v_and_b32_e32 v175, 0xffff0000, v168
	v_lshlrev_b32_e32 v168, 16, v169
	v_and_b32_e32 v169, 0xffff0000, v169
	v_lshlrev_b32_e32 v190, 16, v186
	v_and_b32_e32 v191, 0xffff0000, v186
	v_lshlrev_b32_e32 v186, 16, v187
	v_and_b32_e32 v187, 0xffff0000, v187
	v_lshlrev_b32_e32 v192, 16, v188
	v_and_b32_e32 v193, 0xffff0000, v188
	v_lshlrev_b32_e32 v188, 16, v189
	v_and_b32_e32 v189, 0xffff0000, v189
	v_pk_add_f32 v[126:127], v[126:127], v[166:167]
	v_pk_add_f32 v[124:125], v[124:125], v[170:171]
	v_pk_add_f32 v[122:123], v[122:123], v[168:169]
	v_pk_add_f32 v[120:121], v[120:121], v[174:175]
	v_pk_add_f32 v[118:119], v[118:119], v[186:187]
	v_pk_add_f32 v[116:117], v[116:117], v[190:191]
	v_pk_add_f32 v[114:115], v[114:115], v[188:189]
	v_pk_add_f32 v[112:113], v[112:113], v[192:193]
	v_mul_f32_e32 v166, v125, v125
	v_mul_f32_e32 v167, v127, v127
	v_mul_f32_e32 v168, v121, v121
	v_mul_f32_e32 v169, v123, v123
	v_mul_f32_e32 v170, v117, v117
	v_mul_f32_e32 v171, v119, v119
	v_mul_f32_e32 v174, v113, v113
	v_mul_f32_e32 v175, v115, v115
	v_fmac_f32_e32 v166, v124, v124
	v_fmac_f32_e32 v167, v126, v126
	v_fmac_f32_e32 v168, v120, v120
	v_fmac_f32_e32 v169, v122, v122
	v_fmac_f32_e32 v170, v116, v116
	v_fmac_f32_e32 v171, v118, v118
	v_fmac_f32_e32 v174, v112, v112
	v_fmac_f32_e32 v175, v114, v114
	v_add_f32_e32 v166, v166, v167
	v_add_f32_e32 v167, v168, v169
	v_add_f32_e32 v168, v170, v171
	v_add_f32_e32 v169, v174, v175
	v_cndmask_b32_e32 v160, v182, v160, vcc
	v_add_f32_e32 v166, v166, v167
	v_add_f32_e32 v167, v168, v169
	v_lshlrev_b32_e32 v160, 2, v160
	v_add_f32_e32 v166, v166, v167
	v_mov_b32_e32 v167, v166
	s_nop 1
	v_permlane16_swap_b32_e32 v166, v167
	v_xor_b32_e32 v168, 32, v182
	v_cmp_lt_i32_e32 vcc, v168, v194
	s_waitcnt lgkmcnt(0)
	v_add_f32_e32 v166, v166, v167
	v_cndmask_b32_e32 v168, v182, v168, vcc
	v_lshlrev_b32_e32 v186, 2, v168
	v_mov_b32_e32 v167, v166
	s_nop 1
	v_permlane32_swap_b32_e32 v166, v167
	v_cmp_gt_u32_e32 vcc, 16, v182
	s_and_saveexec_b64 s[20:21], vcc
	s_cbranch_execz .LBB0_980
	s_waitcnt lgkmcnt(0)
	v_add_f32_e32 v166, v166, v167
	v_lshl_add_u32 v167, v182, 4, s44
	ds_write_b32 v167, v166

.LBB0_986:
	s_or_b64 exec, exec, s[20:21]
	v_add_u32_e32 v174, 0x80, v172
	v_ashrrev_i32_e32 v175, 31, v174
	s_waitcnt lgkmcnt(0)
	v_lshlrev_b64 v[64:65], 12, v[174:175]
	v_lshl_add_u64 v[64:65], v[176:177], 0, v[64:65]
	v_add_u32_e32 v170, 0x90, v172
	v_add_u32_e32 v148, 0xa0, v172
	v_add_u32_e32 v128, 0xb0, v172
	v_ashrrev_i32_e32 v171, 31, v170
	v_ashrrev_i32_e32 v149, 31, v148
	v_ashrrev_i32_e32 v129, 31, v128
	v_lshlrev_b64 v[64:65], 12, v[170:171]
	v_lshlrev_b64 v[66:67], 12, v[148:149]
	v_lshlrev_b64 v[68:69], 12, v[128:129]
	v_lshl_add_u64 v[64:65], v[176:177], 0, v[64:65]
	v_lshl_add_u64 v[66:67], v[176:177], 0, v[66:67]
	v_lshl_add_u64 v[176:177], v[176:177], 0, v[68:69]
	global_load_dwordx4 v[68:71], v[176:177], off
	s_nop 0
	global_load_dwordx4 v[64:67], v[176:177], off offset:256
	s_waitcnt vmcnt(7)
	v_lshlrev_b32_e32 v176, 16, v218
	v_and_b32_e32 v177, 0xffff0000, v218
	v_lshlrev_b32_e32 v188, 16, v219
	v_and_b32_e32 v189, 0xffff0000, v219
	v_lshlrev_b32_e32 v196, 16, v220
	v_and_b32_e32 v197, 0xffff0000, v220
	v_lshlrev_b32_e32 v190, 16, v221
	v_and_b32_e32 v191, 0xffff0000, v221
	s_waitcnt vmcnt(6)
	v_lshlrev_b32_e32 v198, 16, v222
	v_and_b32_e32 v199, 0xffff0000, v222
	v_lshlrev_b32_e32 v192, 16, v223
	v_and_b32_e32 v193, 0xffff0000, v223
	v_lshlrev_b32_e32 v200, 16, v224
	v_and_b32_e32 v201, 0xffff0000, v224
	v_lshlrev_b32_e32 v194, 16, v225
	v_and_b32_e32 v195, 0xffff0000, v225
	v_pk_add_f32 v[62:63], v[62:63], v[188:189]
	v_pk_add_f32 v[60:61], v[60:61], v[176:177]
	v_pk_add_f32 v[58:59], v[58:59], v[190:191]
	v_pk_add_f32 v[56:57], v[56:57], v[196:197]
	v_pk_add_f32 v[54:55], v[54:55], v[192:193]
	v_pk_add_f32 v[52:53], v[52:53], v[198:199]
	v_pk_add_f32 v[50:51], v[50:51], v[194:195]
	v_pk_add_f32 v[48:49], v[48:49], v[200:201]
	v_mul_f32_e32 v176, v61, v61
	v_mul_f32_e32 v177, v63, v63
	v_mul_f32_e32 v187, v57, v57
	v_mul_f32_e32 v188, v59, v59
	v_mul_f32_e32 v189, v53, v53
	v_mul_f32_e32 v190, v55, v55
	v_mul_f32_e32 v191, v49, v49
	v_mul_f32_e32 v192, v51, v51
	v_fmac_f32_e32 v176, v60, v60
	v_fmac_f32_e32 v177, v62, v62
	v_fmac_f32_e32 v187, v56, v56
	v_fmac_f32_e32 v188, v58, v58
	v_fmac_f32_e32 v189, v52, v52
	v_fmac_f32_e32 v190, v54, v54
	v_fmac_f32_e32 v191, v48, v48
	v_fmac_f32_e32 v192, v50, v50
	v_add_f32_e32 v176, v176, v177
	v_add_f32_e32 v177, v187, v188
	v_add_f32_e32 v187, v189, v190
	v_add_f32_e32 v188, v191, v192
	v_add_f32_e32 v176, v176, v177
	v_add_f32_e32 v177, v187, v188
	v_add_f32_e32 v176, v176, v177
	v_mov_b32_e32 v177, v176
	s_nop 1
	v_permlane16_swap_b32_e32 v176, v177
	s_waitcnt lgkmcnt(0)
	v_add_f32_e32 v176, v176, v177
	v_mov_b32_e32 v177, v176
	s_nop 1
	v_permlane32_swap_b32_e32 v176, v177
	s_and_saveexec_b64 s[20:21], vcc
	s_cbranch_execz .LBB0_988
	v_lshl_add_u32 v187, v182, 4, s48
	s_waitcnt lgkmcnt(0)
	v_add_f32_e32 v176, v176, v177
	ds_write_b32 v187, v176
.LBB0_988:
	s_or_b64 exec, exec, s[20:21]
	s_waitcnt vmcnt(5)
	v_lshlrev_b32_e32 v176, 16, v226
	s_waitcnt lgkmcnt(0)
	v_and_b32_e32 v177, 0xffff0000, v226
	v_lshlrev_b32_e32 v84, 16, v227
	v_and_b32_e32 v85, 0xffff0000, v227
	v_pk_add_f32 v[46:47], v[46:47], v[84:85]
	v_pk_add_f32 v[44:45], v[44:45], v[176:177]
	v_lshlrev_b32_e32 v188, 16, v228
	v_and_b32_e32 v189, 0xffff0000, v228
	v_lshlrev_b32_e32 v86, 16, v229
	v_and_b32_e32 v87, 0xffff0000, v229
	v_mul_f32_e32 v84, v45, v45
	v_mul_f32_e32 v85, v47, v47
	v_pk_add_f32 v[42:43], v[42:43], v[86:87]
	v_pk_add_f32 v[40:41], v[40:41], v[188:189]
	v_fmac_f32_e32 v84, v44, v44
	v_fmac_f32_e32 v85, v46, v46
	v_add_f32_e32 v84, v84, v85
	v_mul_f32_e32 v85, v41, v41
	v_mul_f32_e32 v86, v43, v43
	v_fmac_f32_e32 v85, v40, v40
	v_fmac_f32_e32 v86, v42, v42
	v_add_f32_e32 v85, v85, v86
	v_add_f32_e32 v176, v84, v85
	s_waitcnt vmcnt(4)
	v_lshlrev_b32_e32 v84, 16, v230
	v_and_b32_e32 v85, 0xffff0000, v230
	v_lshlrev_b32_e32 v80, 16, v231
	v_and_b32_e32 v81, 0xffff0000, v231
	v_pk_add_f32 v[38:39], v[38:39], v[80:81]
	v_pk_add_f32 v[36:37], v[36:37], v[84:85]
	v_lshlrev_b32_e32 v86, 16, v232
	v_and_b32_e32 v87, 0xffff0000, v232
	v_lshlrev_b32_e32 v82, 16, v233
	v_and_b32_e32 v83, 0xffff0000, v233
	v_mul_f32_e32 v80, v37, v37
	v_mul_f32_e32 v81, v39, v39
	v_pk_add_f32 v[34:35], v[34:35], v[82:83]
	v_pk_add_f32 v[32:33], v[32:33], v[86:87]
	v_fmac_f32_e32 v80, v36, v36
	v_fmac_f32_e32 v81, v38, v38
	v_add_f32_e32 v80, v80, v81
	v_mul_f32_e32 v81, v33, v33
	v_mul_f32_e32 v82, v35, v35
	v_fmac_f32_e32 v81, v32, v32
	v_fmac_f32_e32 v82, v34, v34
	v_add_f32_e32 v81, v81, v82
	v_add_f32_e32 v80, v80, v81
	v_add_f32_e32 v80, v176, v80
	v_mov_b32_e32 v81, v80
	s_nop 1
	v_permlane16_swap_b32_e32 v80, v81
	s_waitcnt lgkmcnt(0)
	v_add_f32_e32 v80, v80, v81
	v_mov_b32_e32 v81, v80
	s_nop 1
	v_permlane32_swap_b32_e32 v80, v81
	s_and_saveexec_b64 s[20:21], vcc
	s_cbranch_execz .LBB0_990
	v_lshl_add_u32 v82, v182, 4, s49
	s_waitcnt lgkmcnt(0)
	v_add_f32_e32 v80, v80, v81
	ds_write_b32 v82, v80
.LBB0_990:
	s_or_b64 exec, exec, s[20:21]
	s_waitcnt vmcnt(3)
	v_lshlrev_b32_e32 v80, 16, v234
	s_waitcnt lgkmcnt(0)
	v_and_b32_e32 v81, 0xffff0000, v234
	v_lshlrev_b32_e32 v76, 16, v235
	v_and_b32_e32 v77, 0xffff0000, v235
	v_pk_add_f32 v[30:31], v[30:31], v[76:77]
	v_pk_add_f32 v[28:29], v[28:29], v[80:81]
	v_lshlrev_b32_e32 v82, 16, v236
	v_and_b32_e32 v83, 0xffff0000, v236
	v_lshlrev_b32_e32 v78, 16, v237
	v_and_b32_e32 v79, 0xffff0000, v237
	v_mul_f32_e32 v76, v29, v29
	v_mul_f32_e32 v77, v31, v31
	v_pk_add_f32 v[26:27], v[26:27], v[78:79]
	v_pk_add_f32 v[24:25], v[24:25], v[82:83]
	v_fmac_f32_e32 v76, v28, v28
	v_fmac_f32_e32 v77, v30, v30
	v_add_f32_e32 v76, v76, v77
	v_mul_f32_e32 v77, v25, v25
	v_mul_f32_e32 v78, v27, v27
	v_fmac_f32_e32 v77, v24, v24
	v_fmac_f32_e32 v78, v26, v26
	v_add_f32_e32 v77, v77, v78
	v_add_f32_e32 v80, v76, v77
	s_waitcnt vmcnt(2)
	v_lshlrev_b32_e32 v76, 16, v242
	v_and_b32_e32 v77, 0xffff0000, v242
	v_lshlrev_b32_e32 v72, 16, v243
	v_and_b32_e32 v73, 0xffff0000, v243
	v_pk_add_f32 v[22:23], v[22:23], v[72:73]
	v_pk_add_f32 v[20:21], v[20:21], v[76:77]
	v_lshlrev_b32_e32 v78, 16, v244
	v_and_b32_e32 v79, 0xffff0000, v244
	v_lshlrev_b32_e32 v74, 16, v245
	v_and_b32_e32 v75, 0xffff0000, v245
	v_mul_f32_e32 v72, v21, v21
	v_mul_f32_e32 v73, v23, v23
	v_pk_add_f32 v[18:19], v[18:19], v[74:75]
	v_pk_add_f32 v[16:17], v[16:17], v[78:79]
	v_fmac_f32_e32 v72, v20, v20
	v_fmac_f32_e32 v73, v22, v22
	v_add_f32_e32 v72, v72, v73
	v_mul_f32_e32 v73, v17, v17
	v_mul_f32_e32 v74, v19, v19
	v_fmac_f32_e32 v73, v16, v16
	v_fmac_f32_e32 v74, v18, v18
	v_add_f32_e32 v73, v73, v74
	v_add_f32_e32 v72, v72, v73
	v_add_f32_e32 v72, v80, v72
	v_mov_b32_e32 v73, v72
	s_nop 1
	v_permlane16_swap_b32_e32 v72, v73
	s_waitcnt lgkmcnt(0)
	v_add_f32_e32 v72, v72, v73
	v_mov_b32_e32 v73, v72
	s_nop 1
	v_permlane32_swap_b32_e32 v72, v73
	s_and_saveexec_b64 s[20:21], vcc
	s_cbranch_execz .LBB0_992
	v_lshl_add_u32 v74, v182, 4, s50
	s_waitcnt lgkmcnt(0)
	v_add_f32_e32 v72, v72, v73
	ds_write_b32 v74, v72
